# all five weight-conversion strip loops now prefetch two tiles ahead (in-proj and out-proj strips added), counted vmcnt waits
# speedup vs baseline: 1.0127x; 1.0039x over previous
; #define LAS __attribute__((address_space(3)))
; DI float h2f(bf16_t v) { return (float)__builtin_bit_cast(_Float16, v); }
; DI float bf2f(bf16_t v) { return __uint_as_float(((unsigned)v) << 16); }
; DI void lds_barrier() { asm volatile("s_waitcnt lgkmcnt(0)\n\ts_barrier" ::: "memory"); }
;     ...
;   for (int k0 = kbeg; k0 < kend; k0 += 64) {
;     lds_barrier();
; #pragma unroll
;     for (int rr = 0; rr < 2; ++rr) { const int k = k0 + kr + rr * 32; const float gk = g ? g[k] : 1.0f, bk = b ? b[k] : 0.0f;
; #pragma unroll
;       for (int j = 0; j < 4; ++j) { const bf16_t v = perm ? f2h(w[rr][j] * gk) : f2bf(w[rr][j] * gk); tile[(nc + j) * 72 + kr + rr * 32] = v; s1[j] += perm ? h2f(v) : bf2f(v); s2[j] += bk * w[rr][j]; } }
;     if (k0 + 64 < kend) {
; #pragma unroll
;       for (int rr = 0; rr < 2; ++rr) w[rr] = colok ? *(const f32x4*)(src + (size_t)(k0 + 64 + kr + rr * 32) * ldn + n0 + nc) : (f32x4){0.f, 0.f, 0.f, 0.f};
;     }
;     lds_barrier();
;     { const int n = tid >> 3, kc = (tid & 7) * 8; const int cc = n & 31, slot = (n & 32) + (perm ? 16 * ((cc >> 2) & 1) + 4 * (cc >> 3) + (cc & 3) : cc);
;       *(u32x4*)(dst + (size_t)(dstrow0 + slot) * K + k0 + kc) = *(const LAS u32x4*)(tile + n * 72 + kc); }
;   }
.LBB0_63:
	s_or_b64 exec, exec, s[0:1]
	v_ashrrev_i32_e32 v10, 3, v13
	v_lshrrev_b32_e32 v12, 1, v10
	v_lshlrev_b32_e32 v11, 2, v10
	v_and_b32_e32 v16, 12, v12
	v_mul_lo_u32 v12, v10, s90
	v_and_b32_e32 v10, 35, v10
	v_and_b32_e32 v11, 16, v11
	v_add_u32_e32 v10, s28, v10
	s_ashr_i32 s29, s28, 31
	v_lshlrev_b32_e32 v17, 4, v13
	v_add3_u32 v10, v10, v11, v16
	s_lshl_b64 s[0:1], s[28:29], 2
	v_and_b32_e32 v17, 0x70, v17
	v_ashrrev_i32_e32 v11, 31, v10
	v_lshl_add_u32 v15, v8, 1, 0
	v_add3_u32 v12, 0, v12, v17
	v_lshlrev_b64 v[8:9], 12, v[8:9]
	v_and_b32_e32 v17, 15, v13
	s_add_u32 s0, s45, s0
	v_lshlrev_b64 v[10:11], 11, v[10:11]
	v_and_b32_e32 v13, 7, v13
	v_mul_u32_u24_e32 v14, 0x90, v14
	v_lshl_or_b32 v8, v17, 4, v8
	s_addc_u32 s1, s57, s1
	v_lshl_or_b32 v10, v13, 4, v10
	v_lshl_add_u64 v[8:9], s[0:1], 0, v[8:9]
	v_lshl_add_u64 v[10:11], s[22:23], 0, v[10:11]
	s_mov_b32 s27, 64
	v_add_u32_e32 v13, v15, v14
	v_mov_b32_e32 v224, 0
	v_mov_b32_e32 v225, 0
	v_mov_b32_e32 v226, 0
	v_mov_b32_e32 v227, 0
	v_mov_b32_e32 v220, 0
	v_mov_b32_e32 v221, 0
	v_mov_b32_e32 v222, 0
	v_mov_b32_e32 v223, 0
	s_and_saveexec_b64 s[30:31], s[6:7]
	v_add_co_u32_e32 v224, vcc, 0xfffe0000, v8
	s_nop 1
	v_addc_co_u32_e32 v225, vcc, -1, v9, vcc
	global_load_dwordx4 v[224:227], v[224:225], off
	global_load_dwordx4 v[220:223], v[8:9], off
	s_or_b64 exec, exec, s[30:31]
	s_waitcnt vmcnt(2)
	s_branch .LBB0_66
.LBB0_66:
	v_cvt_f16_f32_e32 v4, v4
	v_cvt_f16_f32_e32 v0, v0
	v_cvt_f16_f32_e32 v5, v5
	v_cvt_f16_f32_e32 v1, v1
	s_waitcnt lgkmcnt(0)
	s_barrier
	v_cvt_f16_f32_e32 v6, v6
	v_cvt_f16_f32_e32 v2, v2
	v_cvt_f16_f32_e32 v7, v7
	v_cvt_f16_f32_e32 v3, v3
	ds_write_b16 v13, v4
	ds_write_b16 v13, v5 offset:144
	ds_write_b16 v13, v6 offset:288
	ds_write_b16 v13, v7 offset:432
	ds_write_b16 v13, v0 offset:64
	ds_write_b16 v13, v1 offset:208
	ds_write_b16 v13, v2 offset:352
	ds_write_b16 v13, v3 offset:496
	s_waitcnt lgkmcnt(0)
	s_barrier
	ds_read_b128 v[14:17], v12
	s_cmpk_gt_u32 s27, 0x3bf
	s_cselect_b64 s[0:1], -1, 0
	s_waitcnt lgkmcnt(0)
	global_store_dwordx4 v[10:11], v[14:17], off offset:-128
	s_and_b64 vcc, exec, s[0:1]
	s_cbranch_vccnz .Lc66_lastq
	v_mov_b32_e32 v4, 0
	v_mov_b32_e32 v5, 0
	v_mov_b32_e32 v6, 0
	v_mov_b32_e32 v7, 0
	v_mov_b32_e32 v0, 0
	v_mov_b32_e32 v1, 0
	v_mov_b32_e32 v2, 0
	v_mov_b32_e32 v3, 0
	s_and_saveexec_b64 s[30:31], s[6:7]
	s_mov_b64 s[98:99], 0x20000
	v_lshl_add_u64 v[4:5], v[8:9], 0, s[98:99]
	global_load_dwordx4 v[4:7], v[4:5], off
	s_mov_b64 s[100:101], 0x40000
	v_lshl_add_u64 v[0:1], v[8:9], 0, s[100:101]
	global_load_dwordx4 v[0:3], v[0:1], off
	s_or_b64 exec, exec, s[30:31]
	s_waitcnt vmcnt(3)
	s_branch .Lc66_q

; #define LAS __attribute__((address_space(3)))
; DI float h2f(bf16_t v) { return (float)__builtin_bit_cast(_Float16, v); }
; DI float bf2f(bf16_t v) { return __uint_as_float(((unsigned)v) << 16); }
; DI void lds_barrier() { asm volatile("s_waitcnt lgkmcnt(0)\n\ts_barrier" ::: "memory"); }
;     ...
;   for (int k0 = kbeg; k0 < kend; k0 += 64) {
;     lds_barrier();
; #pragma unroll
;     for (int rr = 0; rr < 2; ++rr) { const int k = k0 + kr + rr * 32; const float gk = g ? g[k] : 1.0f, bk = b ? b[k] : 0.0f;
; #pragma unroll
;       for (int j = 0; j < 4; ++j) { const bf16_t v = perm ? f2h(w[rr][j] * gk) : f2bf(w[rr][j] * gk); tile[(nc + j) * 72 + kr + rr * 32] = v; s1[j] += perm ? h2f(v) : bf2f(v); s2[j] += bk * w[rr][j]; } }
;     if (k0 + 64 < kend) {
; #pragma unroll
;       for (int rr = 0; rr < 2; ++rr) w[rr] = colok ? *(const f32x4*)(src + (size_t)(k0 + 64 + kr + rr * 32) * ldn + n0 + nc) : (f32x4){0.f, 0.f, 0.f, 0.f};
;     }
;     lds_barrier();
;     { const int n = tid >> 3, kc = (tid & 7) * 8; const int cc = n & 31, slot = (n & 32) + (perm ? 16 * ((cc >> 2) & 1) + 4 * (cc >> 3) + (cc & 3) : cc);
;       *(u32x4*)(dst + (size_t)(dstrow0 + slot) * K + k0 + kc) = *(const LAS u32x4*)(tile + n * 72 + kc); }
;   }
.Lc66_q:
	v_cvt_f16_f32_e32 v18, v224
	v_cvt_f16_f32_e32 v19, v225
	v_cvt_f16_f32_e32 v20, v226
	v_cvt_f16_f32_e32 v21, v227
	v_cvt_f16_f32_e32 v14, v220
	v_cvt_f16_f32_e32 v15, v221
	v_cvt_f16_f32_e32 v16, v222
	v_cvt_f16_f32_e32 v17, v223
	s_waitcnt lgkmcnt(0)
	s_barrier
	ds_write_b16 v13, v18
	ds_write_b16 v13, v19 offset:144
	ds_write_b16 v13, v20 offset:288
	ds_write_b16 v13, v21 offset:432
	ds_write_b16 v13, v14 offset:64
	ds_write_b16 v13, v15 offset:208
	ds_write_b16 v13, v16 offset:352
	ds_write_b16 v13, v17 offset:496
	s_and_b64 vcc, exec, s[0:1]
	s_cbranch_vccnz .Lc66_65
	s_cmpk_lt_u32 s27, 0x380
	s_cbranch_scc0 .Lc66_65
	v_mov_b32_e32 v224, 0
	v_mov_b32_e32 v225, 0
	v_mov_b32_e32 v226, 0
	v_mov_b32_e32 v227, 0
	v_mov_b32_e32 v220, 0
	v_mov_b32_e32 v221, 0
	v_mov_b32_e32 v222, 0
	v_mov_b32_e32 v223, 0
	s_and_saveexec_b64 s[30:31], s[6:7]
	s_mov_b64 s[98:99], 0x60000
	v_lshl_add_u64 v[224:225], v[8:9], 0, s[98:99]
	global_load_dwordx4 v[224:227], v[224:225], off
	s_mov_b64 s[100:101], 0x80000
	v_lshl_add_u64 v[220:221], v[8:9], 0, s[100:101]
	global_load_dwordx4 v[220:223], v[220:221], off
	s_or_b64 exec, exec, s[30:31]
.Lc66_65:
	s_waitcnt lgkmcnt(0)
	s_barrier
	ds_read_b128 v[14:17], v12
	s_mov_b64 s[30:31], 0x80000
	v_lshl_add_u64 v[8:9], v[8:9], 0, s[30:31]
	s_addk_i32 s27, 0x80
	s_andn2_b64 vcc, exec, s[0:1]
	s_waitcnt lgkmcnt(0)
	global_store_dwordx4 v[10:11], v[14:17], off
	v_lshl_add_u64 v[10:11], v[10:11], 0, s[8:9]
	s_cbranch_vccz .LBB0_75
	s_waitcnt vmcnt(3)
	s_branch .LBB0_66

; DI float h2f(bf16_t v) { return (float)__builtin_bit_cast(_Float16, v); }
; DI float bf2f(bf16_t v) { return __uint_as_float(((unsigned)v) << 16); }
; DI void lds_barrier() { asm volatile("s_waitcnt lgkmcnt(0)\n\ts_barrier" ::: "memory"); }
;     ...
;   for (int rr = 0; rr < 2; ++rr) w[rr] = colok ? *(const f32x4*)(src + (size_t)(kbeg + kr + rr * 32) * ldn + n0 + nc) : (f32x4){0.f, 0.f, 0.f, 0.f};
;   for (int k0 = kbeg; k0 < kend; k0 += 64) {
;     lds_barrier();
; #pragma unroll
;     for (int rr = 0; rr < 2; ++rr) { const int k = k0 + kr + rr * 32; const float gk = g ? g[k] : 1.0f, bk = b ? b[k] : 0.0f;
; #pragma unroll
;       for (int j = 0; j < 4; ++j) { const bf16_t v = perm ? f2h(w[rr][j] * gk) : f2bf(w[rr][j] * gk); tile[(nc + j) * 72 + kr + rr * 32] = v; s1[j] += perm ? h2f(v) : bf2f(v); s2[j] += bk * w[rr][j]; } }
;     if (k0 + 64 < kend) {
; #pragma unroll
;       for (int rr = 0; rr < 2; ++rr) w[rr] = colok ? *(const f32x4*)(src + (size_t)(k0 + 64 + kr + rr * 32) * ldn + n0 + nc) : (f32x4){0.f, 0.f, 0.f, 0.f};
;     }
.Lconv83_nb0:
	s_waitcnt vmcnt(0)
	v_mov_b32_e32 v244, 0
	v_mov_b32_e32 v245, 0
	v_mov_b32_e32 v246, 0
	v_mov_b32_e32 v247, 0
	v_mov_b32_e32 v248, 0
	v_mov_b32_e32 v249, 0
	v_mov_b32_e32 v250, 0
	v_mov_b32_e32 v251, 0
	s_and_saveexec_b64 s[30:31], s[6:7]
	v_lshl_add_u64 v[244:245], v[34:35], 0, v[30:31]
	v_lshl_add_u64 v[248:249], v[34:35], 0, v[36:37]
	global_load_dwordx4 v[244:247], v[244:245], off
	s_nop 0
	global_load_dwordx4 v[248:251], v[248:249], off
	s_or_b64 exec, exec, s[30:31]

; DI float h2f(bf16_t v) { return (float)__builtin_bit_cast(_Float16, v); }
; DI float bf2f(bf16_t v) { return __uint_as_float(((unsigned)v) << 16); }
;     ...
;     for (int rr = 0; rr < 2; ++rr) { const int k = k0 + kr + rr * 32; const float gk = g ? g[k] : 1.0f, bk = b ? b[k] : 0.0f;
; #pragma unroll
;       for (int j = 0; j < 4; ++j) { const bf16_t v = perm ? f2h(w[rr][j] * gk) : f2bf(w[rr][j] * gk); tile[(nc + j) * 72 + kr + rr * 32] = v; s1[j] += perm ? h2f(v) : bf2f(v); s2[j] += bk * w[rr][j]; } }
.Lc83a_87:
	v_fma_mixlo_f16 v43, v0, v16, 0
	v_fma_mixlo_f16 v45, v1, v16, 0
	v_fma_mixlo_f16 v46, v2, v16, 0
	v_fma_mixlo_f16 v47, v3, v16, 0
	s_andn2_b64 vcc, exec, s[4:5]
	v_mov_b32_e32 v16, 1.0
	ds_write_b16 v25, v43
	ds_write_b16 v25, v45 offset:144
	ds_write_b16 v25, v46 offset:288
	ds_write_b16 v25, v47 offset:432
	s_cbranch_vccnz .Lc83a_89
	v_mov_b32_e32 v16, v218

; DI float h2f(bf16_t v) { return (float)__builtin_bit_cast(_Float16, v); }
; DI float bf2f(bf16_t v) { return __uint_as_float(((unsigned)v) << 16); }
;     ...
;     for (int rr = 0; rr < 2; ++rr) { const int k = k0 + kr + rr * 32; const float gk = g ? g[k] : 1.0f, bk = b ? b[k] : 0.0f;
; #pragma unroll
;       for (int j = 0; j < 4; ++j) { const bf16_t v = perm ? f2h(w[rr][j] * gk) : f2bf(w[rr][j] * gk); tile[(nc + j) * 72 + kr + rr * 32] = v; s1[j] += perm ? h2f(v) : bf2f(v); s2[j] += bk * w[rr][j]; } }
;     if (k0 + 64 < kend) {
; #pragma unroll
;       for (int rr = 0; rr < 2; ++rr) w[rr] = colok ? *(const f32x4*)(src + (size_t)(k0 + 64 + kr + rr * 32) * ldn + n0 + nc) : (f32x4){0.f, 0.f, 0.f, 0.f};
;     }
.Lc83a_91:
	s_cmpk_gt_u32 s27, 0x3bf
	v_fma_mixlo_f16 v48, v4, v16, 0
	v_fma_mixlo_f16 v49, v5, v16, 0
	v_fma_mixlo_f16 v50, v6, v16, 0
	v_fma_mixlo_f16 v51, v7, v16, 0
	s_cselect_b64 s[0:1], -1, 0
	s_cmpk_lt_u32 s27, 0x3c0
	ds_write_b16 v25, v48 offset:64
	ds_write_b16 v25, v49 offset:208
	ds_write_b16 v25, v50 offset:352
	ds_write_b16 v25, v51 offset:496
	s_cbranch_scc0 .Lc83a_97
	s_and_b64 vcc, exec, s[4:5]
	s_cbranch_vccz .Lc83a_ng
	global_load_dword v216, v[40:41], off offset:256
	global_load_dword v218, v[40:41], off offset:384

; #define LAS __attribute__((address_space(3)))
; DI float h2f(bf16_t v) { return (float)__builtin_bit_cast(_Float16, v); }
; DI float bf2f(bf16_t v) { return __uint_as_float(((unsigned)v) << 16); }
; DI void lds_barrier() { asm volatile("s_waitcnt lgkmcnt(0)\n\ts_barrier" ::: "memory"); }
;     ...
;   for (int k0 = kbeg; k0 < kend; k0 += 64) {
;     lds_barrier();
; #pragma unroll
;     for (int rr = 0; rr < 2; ++rr) { const int k = k0 + kr + rr * 32; const float gk = g ? g[k] : 1.0f, bk = b ? b[k] : 0.0f;
; #pragma unroll
;       for (int j = 0; j < 4; ++j) { const bf16_t v = perm ? f2h(w[rr][j] * gk) : f2bf(w[rr][j] * gk); tile[(nc + j) * 72 + kr + rr * 32] = v; s1[j] += perm ? h2f(v) : bf2f(v); s2[j] += bk * w[rr][j]; } }
;     if (k0 + 64 < kend) {
; #pragma unroll
;       for (int rr = 0; rr < 2; ++rr) w[rr] = colok ? *(const f32x4*)(src + (size_t)(k0 + 64 + kr + rr * 32) * ldn + n0 + nc) : (f32x4){0.f, 0.f, 0.f, 0.f};
;     }
;     lds_barrier();
;     { const int n = tid >> 3, kc = (tid & 7) * 8; const int cc = n & 31, slot = (n & 32) + (perm ? 16 * ((cc >> 2) & 1) + 4 * (cc >> 3) + (cc & 3) : cc);
;       *(u32x4*)(dst + (size_t)(dstrow0 + slot) * K + k0 + kc) = *(const LAS u32x4*)(tile + n * 72 + kc); }
;   }
.Lc83a_nb:
	s_cmpk_lt_u32 s27, 0x380
	s_cbranch_scc0 .Lc83a_97
	v_mov_b32_e32 v220, 0
	v_mov_b32_e32 v221, 0
	v_mov_b32_e32 v222, 0
	v_mov_b32_e32 v223, 0
	v_mov_b32_e32 v224, 0
	v_mov_b32_e32 v225, 0
	v_mov_b32_e32 v226, 0
	v_mov_b32_e32 v227, 0
	s_and_saveexec_b64 s[30:31], s[6:7]
	v_lshl_add_u64 v[220:221], v[34:35], 0, v[30:31]
	v_lshl_add_u64 v[224:225], v[34:35], 0, v[36:37]
	v_lshl_add_u64 v[220:221], v[220:221], 0, s[82:83]
	v_lshl_add_u64 v[224:225], v[224:225], 0, s[82:83]
	global_load_dwordx4 v[220:223], v[220:221], off
	s_nop 0
	global_load_dwordx4 v[224:227], v[224:225], off
	s_or_b64 exec, exec, s[30:31]
.Lc83a_97:
	v_cvt_f32_f16_e32 v46, v46
	v_cvt_f32_f16_e32 v47, v47
	v_cvt_f32_f16_e32 v43, v43
	v_cvt_f32_f16_e32 v45, v45
	v_add_f32_e32 v10, v10, v46
	v_add_f32_e32 v11, v11, v47
	v_cvt_f32_f16_e32 v46, v50
	v_cvt_f32_f16_e32 v47, v51
	s_waitcnt lgkmcnt(0)
	s_barrier
	v_add_f32_e32 v8, v8, v43
	v_add_f32_e32 v9, v9, v45
	v_cvt_f32_f16_e32 v43, v48
	v_cvt_f32_f16_e32 v45, v49
	v_add_f32_e32 v10, v10, v46
	v_add_f32_e32 v11, v11, v47
	ds_read_b128 v[46:49], v27
	v_pk_fma_f32 v[0:1], v[0:1], v[42:43], v[12:13] op_sel_hi:[1,0,1]
	v_pk_fma_f32 v[2:3], v[2:3], v[42:43], v[14:15] op_sel_hi:[1,0,1]
	v_add_f32_e32 v8, v8, v43
	v_add_f32_e32 v9, v9, v45
	v_pk_fma_f32 v[12:13], v[4:5], v[44:45], v[0:1] op_sel_hi:[1,0,1]
	v_pk_fma_f32 v[14:15], v[6:7], v[44:45], v[2:3] op_sel_hi:[1,0,1]
	s_add_i32 s27, s27, 64
	s_waitcnt lgkmcnt(0)
	global_store_dwordx4 v[28:29], v[46:49], off
	v_lshl_add_u64 v[28:29], v[28:29], 0, s[2:3]
	v_lshl_add_u64 v[34:35], v[34:35], 0, s[82:83]
	v_lshl_add_u64 v[38:39], v[38:39], 0, s[8:9]
	v_lshl_add_u64 v[40:41], v[40:41], 0, s[8:9]
	s_and_b64 vcc, exec, s[0:1]
	s_cbranch_vccnz .LBB0_99
	s_cmpk_lt_u32 s27, 0x3c0
	s_cbranch_scc1 .Lc83a_w3
	s_waitcnt vmcnt(1)
	s_branch .Lc83a_cp

; DI float h2f(bf16_t v) { return (float)__builtin_bit_cast(_Float16, v); }
; DI float bf2f(bf16_t v) { return __uint_as_float(((unsigned)v) << 16); }
; DI void lds_barrier() { asm volatile("s_waitcnt lgkmcnt(0)\n\ts_barrier" ::: "memory"); }
;     ...
;   for (int k0 = kbeg; k0 < kend; k0 += 64) {
;     lds_barrier();
; #pragma unroll
;     for (int rr = 0; rr < 2; ++rr) { const int k = k0 + kr + rr * 32; const float gk = g ? g[k] : 1.0f, bk = b ? b[k] : 0.0f;
; #pragma unroll
;       for (int j = 0; j < 4; ++j) { const bf16_t v = perm ? f2h(w[rr][j] * gk) : f2bf(w[rr][j] * gk); tile[(nc + j) * 72 + kr + rr * 32] = v; s1[j] += perm ? h2f(v) : bf2f(v); s2[j] += bk * w[rr][j]; } }
.Lc83a_cp:
	v_mov_b32_e32 v0, v244
	v_mov_b32_e32 v1, v245
	v_mov_b32_e32 v2, v246
	v_mov_b32_e32 v3, v247
	v_mov_b32_e32 v4, v248
	v_mov_b32_e32 v5, v249
	v_mov_b32_e32 v6, v250
	v_mov_b32_e32 v7, v251
.Lc83b_top:
	s_waitcnt lgkmcnt(0)
	s_barrier
	v_mov_b32_e32 v16, 1.0
	s_and_b64 vcc, exec, s[4:5]
	s_cbranch_vccz .Lc83b_85
	v_mov_b32_e32 v16, v216

;     ...
;     if (k0 + 64 < kend) {
; #pragma unroll
;       for (int rr = 0; rr < 2; ++rr) w[rr] = colok ? *(const f32x4*)(src + (size_t)(k0 + 64 + kr + rr * 32) * ldn + n0 + nc) : (f32x4){0.f, 0.f, 0.f, 0.f};
;     }
.Lc83b_nb:
	s_cmpk_lt_u32 s27, 0x380
	s_cbranch_scc0 .Lc83b_97
	v_mov_b32_e32 v244, 0
	v_mov_b32_e32 v245, 0
	v_mov_b32_e32 v246, 0
	v_mov_b32_e32 v247, 0
	v_mov_b32_e32 v248, 0
	v_mov_b32_e32 v249, 0
	v_mov_b32_e32 v250, 0
	v_mov_b32_e32 v251, 0
	s_and_saveexec_b64 s[30:31], s[6:7]
	v_lshl_add_u64 v[244:245], v[34:35], 0, v[30:31]
	v_lshl_add_u64 v[248:249], v[34:35], 0, v[36:37]
	v_lshl_add_u64 v[244:245], v[244:245], 0, s[82:83]
	v_lshl_add_u64 v[248:249], v[248:249], 0, s[82:83]
	global_load_dwordx4 v[244:247], v[244:245], off
	s_nop 0
	global_load_dwordx4 v[248:251], v[248:249], off
	s_or_b64 exec, exec, s[30:31]

;     ...
;   if (c1) {
;     __syncthreads();
; #pragma unroll
;     for (int j = 0; j < 4; ++j) { red[kr * 64 + nc + j] = s1[j]; red[2048 + kr * 64 + nc + j] = s2[j]; }
;     __syncthreads();
;     if (tid < 128) { const int n = tid & 63, which = tid >> 6; float s = 0.f; for (int i = 0; i < 32; ++i) s += red[which * 2048 + i * 64 + n]; (which ? c2 : c1)[dstrow0 + n] = s; }
;   }
.Lc83b_cp:
	v_mov_b32_e32 v0, v220
	v_mov_b32_e32 v1, v221
	v_mov_b32_e32 v2, v222
	v_mov_b32_e32 v3, v223
	v_mov_b32_e32 v4, v224
	v_mov_b32_e32 v5, v225
	v_mov_b32_e32 v6, v226
	v_mov_b32_e32 v7, v227
	s_branch .LBB0_83
.LBB0_99:
	v_lshlrev_b32_e32 v0, 8, v24
	v_add3_u32 v0, 0, v0, v26
	v_cmp_gt_i32_e32 vcc, s96, v33
	s_barrier
	ds_write_b128 v0, v[8:11] offset:9216
	ds_write_b128 v0, v[12:15] offset:17408
	s_waitcnt lgkmcnt(0)
	s_barrier
	s_and_saveexec_b64 s[0:1], vcc
	s_cbranch_execz .LBB0_101
	v_and_b32_e32 v8, 63, v33
	v_lshlrev_b32_e32 v0, 7, v33
	v_and_b32_e32 v0, 0xffffe000, v0
	v_lshlrev_b32_e32 v1, 2, v8
	v_add3_u32 v9, 0, v0, v1
	ds_read2st64_b32 v[0:1], v9 offset0:36 offset1:37
	ds_read2st64_b32 v[2:3], v9 offset0:38 offset1:39
	ds_read2st64_b32 v[4:5], v9 offset0:40 offset1:41
	ds_read2st64_b32 v[6:7], v9 offset0:42 offset1:43
	v_cmp_gt_u32_e32 vcc, 64, v33
	s_waitcnt lgkmcnt(3)
	v_add_f32_e32 v0, 0, v0
	v_add_f32_e32 v0, v0, v1
	s_waitcnt lgkmcnt(2)
	v_add_f32_e32 v0, v0, v2
	v_add_f32_e32 v0, v0, v3
	s_waitcnt lgkmcnt(1)
	v_add_f32_e32 v0, v0, v4
	v_add_f32_e32 v0, v0, v5
	s_waitcnt lgkmcnt(0)
	v_add_f32_e32 v2, v0, v6
	ds_read2st64_b32 v[0:1], v9 offset0:44 offset1:45
	v_add_f32_e32 v10, v2, v7
	ds_read2st64_b32 v[2:3], v9 offset0:46 offset1:47
	ds_read2st64_b32 v[4:5], v9 offset0:48 offset1:49
	ds_read2st64_b32 v[6:7], v9 offset0:50 offset1:51
	s_waitcnt lgkmcnt(3)
	v_add_f32_e32 v0, v10, v0
	v_add_f32_e32 v0, v0, v1
	s_waitcnt lgkmcnt(2)
	v_add_f32_e32 v0, v0, v2
	v_add_f32_e32 v0, v0, v3
	s_waitcnt lgkmcnt(1)
	v_add_f32_e32 v0, v0, v4
	v_add_f32_e32 v0, v0, v5
	s_waitcnt lgkmcnt(0)
	v_add_f32_e32 v2, v0, v6
	ds_read2st64_b32 v[0:1], v9 offset0:52 offset1:53
	v_add_f32_e32 v10, v2, v7
	ds_read2st64_b32 v[2:3], v9 offset0:54 offset1:55
	ds_read2st64_b32 v[4:5], v9 offset0:56 offset1:57
	ds_read2st64_b32 v[6:7], v9 offset0:58 offset1:59
	s_waitcnt lgkmcnt(3)
	v_add_f32_e32 v0, v10, v0
	v_add_f32_e32 v0, v0, v1
	s_waitcnt lgkmcnt(2)
	v_add_f32_e32 v0, v0, v2
	v_add_f32_e32 v0, v0, v3
	s_waitcnt lgkmcnt(1)
	v_add_f32_e32 v0, v0, v4
	v_add_f32_e32 v0, v0, v5
	s_waitcnt lgkmcnt(0)
	v_add_f32_e32 v2, v0, v6
	ds_read2st64_b32 v[0:1], v9 offset0:60 offset1:61
	v_add_f32_e32 v10, v2, v7
	ds_read2st64_b32 v[2:3], v9 offset0:62 offset1:63
	ds_read2st64_b32 v[4:5], v9 offset0:64 offset1:65
	ds_read2st64_b32 v[6:7], v9 offset0:66 offset1:67
	s_waitcnt lgkmcnt(3)
	v_add_f32_e32 v0, v10, v0
	v_add_f32_e32 v0, v0, v1
	s_waitcnt lgkmcnt(2)
	v_add_f32_e32 v0, v0, v2
	v_add_f32_e32 v0, v0, v3
	s_waitcnt lgkmcnt(1)
	v_add_f32_e32 v0, v0, v4
	v_add_f32_e32 v0, v0, v5
	s_waitcnt lgkmcnt(0)
	v_add_f32_e32 v0, v0, v6
	v_add_f32_e32 v4, v0, v7
	v_cndmask_b32_e32 v0, v234, v235, vcc
	v_mov_b32_e32 v1, v32
	v_lshl_add_u64 v[0:1], s[94:95], 0, v[0:1]
	v_or_b32_e32 v2, s84, v8
	v_mov_b32_e32 v3, v32
	v_lshl_add_u64 v[0:1], v[2:3], 2, v[0:1]
	global_store_dword v[0:1], v4, off
